# o29 + w_o weight conversion (128 filler pulls) moved from the filler queue into the GU1 idle-tail wave queue (after the w1d pairs)
# speedup vs baseline: 1.0296x; 1.0022x over previous
.Lw1d_go:
	v_readlane_b32 s0, v253, 21
	v_readlane_b32 s1, v253, 22
	s_nop 3
	s_sub_u32 s0, s0, 0xe0
	s_subb_u32 s1, s1, 0
	s_load_dwordx2 s[8:9], s[0:1], 0x50
	s_load_dwordx2 s[10:11], s[0:1], 0x90
	s_add_u32 s6, s86, 0xc600
	s_addc_u32 s7, s87, 0
	v_and_b32_e32 v6, 15, v0
	v_and_b32_e32 v7, 48, v0
	v_lshlrev_b32_e32 v8, 13, v7
	v_lshl_or_b32 v8, v6, 4, v8
	v_lshlrev_b32_e32 v9, 2, v6
	v_and_b32_e32 v9, 32, v9
	v_lshlrev_b32_e32 v10, 4, v6
	v_and_b32_e32 v10, 16, v10
	v_lshlrev_b32_e32 v11, 1, v6
	v_and_b32_e32 v11, 12, v11
	v_or3_b32 v9, v9, v10, v11
	v_lshlrev_b32_e32 v44, 12, v9
	v_lshl_add_u32 v44, v7, 1, v44
	v_add_u32_e32 v45, 0x1000, v44
	v_add_u32_e32 v46, 0x2000, v44
	v_add_u32_e32 v47, 0x3000, v44
	v_mul_u32_u24_e32 v9, 0x2c00, v9
	v_lshl_add_u32 v12, v7, 1, v9
	v_add_u32_e32 v13, 0x2c00, v12
	v_add_u32_e32 v14, 0x5800, v12
	v_add_u32_e32 v15, 0x8400, v12
	v_mov_b32_e32 v16, 0
	v_mov_b32_e32 v17, 1
	s_mov_b64 exec, 1
	global_atomic_add v18, v16, v17, s[6:7] sc0
	s_mov_b64 exec, -1
	s_waitcnt vmcnt(0) lgkmcnt(0)
.Lw1d_loop:
	v_readfirstlane_b32 s98, v18
	s_nop 3
	s_cmpk_ge_u32 s98, 0x780
	s_cbranch_scc1 .Lw1d_done
	s_cmpk_ge_u32 s98, 0x580
	s_cbranch_scc1 .Lwo_item
	s_lshr_b32 s99, s98, 4
	s_and_b32 s100, s98, 15
	s_lshl_b32 s101, s99, 19
	s_lshl_b32 s0, s100, 9
	s_add_u32 s0, s0, s101
	s_add_u32 s0, s8, s0
	s_addc_u32 s1, s9, 0
	s_mul_i32 s2, s100, 0x160000
	s_lshl_b32 s3, s99, 7
	s_add_u32 s2, s2, s3
	s_add_u32 s2, s2, 0x2d60200
	s_add_u32 s2, s86, s2
	s_addc_u32 s3, s87, 0
	s_add_u32 s4, s2, 0xb0000
	s_addc_u32 s5, s3, 0
	global_load_dwordx4 v[154:157], v8, s[0:1] nt
	global_load_dwordx4 v[204:207], v8, s[0:1] offset:256 nt
	s_add_u32 s0, s0, 0x2000
	s_addc_u32 s1, s1, 0
	global_load_dwordx4 v[158:161], v8, s[0:1] nt
	global_load_dwordx4 v[208:211], v8, s[0:1] offset:256 nt
	s_add_u32 s0, s0, 0x2000
	s_addc_u32 s1, s1, 0
	global_load_dwordx4 v[162:165], v8, s[0:1] nt
	global_load_dwordx4 v[212:215], v8, s[0:1] offset:256 nt
	s_add_u32 s0, s0, 0x2000
	s_addc_u32 s1, s1, 0
	global_load_dwordx4 v[166:169], v8, s[0:1] nt
	global_load_dwordx4 v[216:219], v8, s[0:1] offset:256 nt
	s_add_u32 s0, s0, 0x2000
	s_addc_u32 s1, s1, 0
	global_load_dwordx4 v[170:173], v8, s[0:1] nt
	global_load_dwordx4 v[220:223], v8, s[0:1] offset:256 nt
	s_add_u32 s0, s0, 0x2000
	s_addc_u32 s1, s1, 0
	global_load_dwordx4 v[174:177], v8, s[0:1] nt
	global_load_dwordx4 v[224:227], v8, s[0:1] offset:256 nt
	s_add_u32 s0, s0, 0x2000
	s_addc_u32 s1, s1, 0
	global_load_dwordx4 v[178:181], v8, s[0:1] nt
	global_load_dwordx4 v[228:231], v8, s[0:1] offset:256 nt
	s_add_u32 s0, s0, 0x2000
	s_addc_u32 s1, s1, 0
	global_load_dwordx4 v[182:185], v8, s[0:1] nt
	global_load_dwordx4 v[232:235], v8, s[0:1] offset:256 nt
	s_add_u32 s0, s0, 0x2000
	s_addc_u32 s1, s1, 0
	global_load_dwordx4 v[186:189], v8, s[0:1] nt
	global_load_dwordx4 v[236:239], v8, s[0:1] offset:256 nt
	s_add_u32 s0, s0, 0x2000
	s_addc_u32 s1, s1, 0
	global_load_dwordx4 v[190:193], v8, s[0:1] nt
	global_load_dwordx4 v[240:243], v8, s[0:1] offset:256 nt
	s_add_u32 s0, s0, 0x2000
	s_addc_u32 s1, s1, 0
	global_load_dwordx4 v[194:197], v8, s[0:1] nt
	global_load_dwordx4 v[244:247], v8, s[0:1] offset:256 nt
	s_add_u32 s0, s0, 0x2000
	s_addc_u32 s1, s1, 0
	global_load_dwordx4 v[198:201], v8, s[0:1] nt
	global_load_dwordx4 v[248:251], v8, s[0:1] offset:256 nt
	s_add_u32 s0, s0, 0x2000
	s_addc_u32 s1, s1, 0
	global_load_dwordx4 v[130:133], v8, s[0:1] nt
	global_load_dwordx4 v[50:53], v8, s[0:1] offset:256 nt
	s_add_u32 s0, s0, 0x2000
	s_addc_u32 s1, s1, 0
	global_load_dwordx4 v[134:137], v8, s[0:1] nt
	global_load_dwordx4 v[54:57], v8, s[0:1] offset:256 nt
	s_add_u32 s0, s0, 0x2000
	s_addc_u32 s1, s1, 0
	global_load_dwordx4 v[138:141], v8, s[0:1] nt
	global_load_dwordx4 v[58:61], v8, s[0:1] offset:256 nt
	s_add_u32 s0, s0, 0x2000
	s_addc_u32 s1, s1, 0
	global_load_dwordx4 v[142:145], v8, s[0:1] nt
	global_load_dwordx4 v[62:65], v8, s[0:1] offset:256 nt
	s_mov_b64 exec, 1
	global_atomic_add v18, v16, v17, s[6:7] sc0
	s_mov_b64 exec, -1
	s_waitcnt vmcnt(1)
	v_cvt_pk_bf16_f32 v20, v154, v158
	v_cvt_pk_bf16_f32 v21, v162, v166
	v_cvt_pk_bf16_f32 v22, v170, v174
	v_cvt_pk_bf16_f32 v23, v178, v182
	global_store_dwordx4 v12, v[20:23], s[2:3]
	v_cvt_pk_bf16_f32 v24, v186, v190
	v_cvt_pk_bf16_f32 v25, v194, v198
	v_cvt_pk_bf16_f32 v26, v130, v134
	v_cvt_pk_bf16_f32 v27, v138, v142
	global_store_dwordx4 v12, v[24:27], s[2:3] offset:16
	v_cvt_pk_bf16_f32 v28, v155, v159
	v_cvt_pk_bf16_f32 v29, v163, v167
	v_cvt_pk_bf16_f32 v30, v171, v175
	v_cvt_pk_bf16_f32 v31, v179, v183
	global_store_dwordx4 v13, v[28:31], s[2:3]
	v_cvt_pk_bf16_f32 v32, v187, v191
	v_cvt_pk_bf16_f32 v33, v195, v199
	v_cvt_pk_bf16_f32 v34, v131, v135
	v_cvt_pk_bf16_f32 v35, v139, v143
	global_store_dwordx4 v13, v[32:35], s[2:3] offset:16
	v_cvt_pk_bf16_f32 v36, v156, v160
	v_cvt_pk_bf16_f32 v37, v164, v168
	v_cvt_pk_bf16_f32 v38, v172, v176
	v_cvt_pk_bf16_f32 v39, v180, v184
	global_store_dwordx4 v14, v[36:39], s[2:3]
	v_cvt_pk_bf16_f32 v40, v188, v192
	v_cvt_pk_bf16_f32 v41, v196, v200
	v_cvt_pk_bf16_f32 v42, v132, v136
	v_cvt_pk_bf16_f32 v43, v140, v144
	global_store_dwordx4 v14, v[40:43], s[2:3] offset:16
	v_cvt_pk_bf16_f32 v20, v157, v161
	v_cvt_pk_bf16_f32 v21, v165, v169
	v_cvt_pk_bf16_f32 v22, v173, v177
	v_cvt_pk_bf16_f32 v23, v181, v185
	global_store_dwordx4 v15, v[20:23], s[2:3]
	v_cvt_pk_bf16_f32 v24, v189, v193
	v_cvt_pk_bf16_f32 v25, v197, v201
	v_cvt_pk_bf16_f32 v26, v133, v137
	v_cvt_pk_bf16_f32 v27, v141, v145
	global_store_dwordx4 v15, v[24:27], s[2:3] offset:16
	v_cvt_pk_bf16_f32 v28, v204, v208
	v_cvt_pk_bf16_f32 v29, v212, v216
	v_cvt_pk_bf16_f32 v30, v220, v224
	v_cvt_pk_bf16_f32 v31, v228, v232
	global_store_dwordx4 v12, v[28:31], s[4:5]
	v_cvt_pk_bf16_f32 v32, v236, v240
	v_cvt_pk_bf16_f32 v33, v244, v248
	v_cvt_pk_bf16_f32 v34, v50, v54
	v_cvt_pk_bf16_f32 v35, v58, v62
	global_store_dwordx4 v12, v[32:35], s[4:5] offset:16
	v_cvt_pk_bf16_f32 v36, v205, v209
	v_cvt_pk_bf16_f32 v37, v213, v217
	v_cvt_pk_bf16_f32 v38, v221, v225
	v_cvt_pk_bf16_f32 v39, v229, v233
	global_store_dwordx4 v13, v[36:39], s[4:5]
	v_cvt_pk_bf16_f32 v40, v237, v241
	v_cvt_pk_bf16_f32 v41, v245, v249
	v_cvt_pk_bf16_f32 v42, v51, v55
	v_cvt_pk_bf16_f32 v43, v59, v63
	global_store_dwordx4 v13, v[40:43], s[4:5] offset:16
	v_cvt_pk_bf16_f32 v20, v206, v210
	v_cvt_pk_bf16_f32 v21, v214, v218
	v_cvt_pk_bf16_f32 v22, v222, v226
	v_cvt_pk_bf16_f32 v23, v230, v234
	global_store_dwordx4 v14, v[20:23], s[4:5]
	v_cvt_pk_bf16_f32 v24, v238, v242
	v_cvt_pk_bf16_f32 v25, v246, v250
	v_cvt_pk_bf16_f32 v26, v52, v56
	v_cvt_pk_bf16_f32 v27, v60, v64
	global_store_dwordx4 v14, v[24:27], s[4:5] offset:16
	v_cvt_pk_bf16_f32 v28, v207, v211
	v_cvt_pk_bf16_f32 v29, v215, v219
	v_cvt_pk_bf16_f32 v30, v223, v227
	v_cvt_pk_bf16_f32 v31, v231, v235
	global_store_dwordx4 v15, v[28:31], s[4:5]
	v_cvt_pk_bf16_f32 v32, v239, v243
	v_cvt_pk_bf16_f32 v33, v247, v251
	v_cvt_pk_bf16_f32 v34, v53, v57
	v_cvt_pk_bf16_f32 v35, v61, v65
	global_store_dwordx4 v15, v[32:35], s[4:5] offset:16
	s_waitcnt vmcnt(16)
	s_branch .Lw1d_loop
.Lwo_item:
	s_sub_u32 s98, s98, 0x580
	s_lshr_b32 s99, s98, 4
	s_and_b32 s100, s98, 15
	s_lshl_b32 s101, s99, 19
	s_lshl_b32 s0, s100, 9
	s_add_u32 s0, s0, s101
	s_add_u32 s0, s10, s0
	s_addc_u32 s1, s11, 0
	s_lshl_b32 s2, s100, 19
	s_lshl_b32 s3, s99, 7
	s_add_u32 s2, s2, s3
	s_add_u32 s2, s2, 0x8460200
	s_add_u32 s2, s86, s2
	s_addc_u32 s3, s87, 0
	s_add_u32 s4, s2, 0x40000
	s_addc_u32 s5, s3, 0
	global_load_dwordx4 v[154:157], v8, s[0:1] nt
	global_load_dwordx4 v[204:207], v8, s[0:1] offset:256 nt
	s_add_u32 s0, s0, 0x2000
	s_addc_u32 s1, s1, 0
	global_load_dwordx4 v[158:161], v8, s[0:1] nt
	global_load_dwordx4 v[208:211], v8, s[0:1] offset:256 nt
	s_add_u32 s0, s0, 0x2000
	s_addc_u32 s1, s1, 0
	global_load_dwordx4 v[162:165], v8, s[0:1] nt
	global_load_dwordx4 v[212:215], v8, s[0:1] offset:256 nt
	s_add_u32 s0, s0, 0x2000
	s_addc_u32 s1, s1, 0
	global_load_dwordx4 v[166:169], v8, s[0:1] nt
	global_load_dwordx4 v[216:219], v8, s[0:1] offset:256 nt
	s_add_u32 s0, s0, 0x2000
	s_addc_u32 s1, s1, 0
	global_load_dwordx4 v[170:173], v8, s[0:1] nt
	global_load_dwordx4 v[220:223], v8, s[0:1] offset:256 nt
	s_add_u32 s0, s0, 0x2000
	s_addc_u32 s1, s1, 0
	global_load_dwordx4 v[174:177], v8, s[0:1] nt
	global_load_dwordx4 v[224:227], v8, s[0:1] offset:256 nt
	s_add_u32 s0, s0, 0x2000
	s_addc_u32 s1, s1, 0
	global_load_dwordx4 v[178:181], v8, s[0:1] nt
	global_load_dwordx4 v[228:231], v8, s[0:1] offset:256 nt
	s_add_u32 s0, s0, 0x2000
	s_addc_u32 s1, s1, 0
	global_load_dwordx4 v[182:185], v8, s[0:1] nt
	global_load_dwordx4 v[232:235], v8, s[0:1] offset:256 nt
	s_add_u32 s0, s0, 0x2000
	s_addc_u32 s1, s1, 0
	global_load_dwordx4 v[186:189], v8, s[0:1] nt
	global_load_dwordx4 v[236:239], v8, s[0:1] offset:256 nt
	s_add_u32 s0, s0, 0x2000
	s_addc_u32 s1, s1, 0
	global_load_dwordx4 v[190:193], v8, s[0:1] nt
	global_load_dwordx4 v[240:243], v8, s[0:1] offset:256 nt
	s_add_u32 s0, s0, 0x2000
	s_addc_u32 s1, s1, 0
	global_load_dwordx4 v[194:197], v8, s[0:1] nt
	global_load_dwordx4 v[244:247], v8, s[0:1] offset:256 nt
	s_add_u32 s0, s0, 0x2000
	s_addc_u32 s1, s1, 0
	global_load_dwordx4 v[198:201], v8, s[0:1] nt
	global_load_dwordx4 v[248:251], v8, s[0:1] offset:256 nt
	s_add_u32 s0, s0, 0x2000
	s_addc_u32 s1, s1, 0
	global_load_dwordx4 v[130:133], v8, s[0:1] nt
	global_load_dwordx4 v[50:53], v8, s[0:1] offset:256 nt
	s_add_u32 s0, s0, 0x2000
	s_addc_u32 s1, s1, 0
	global_load_dwordx4 v[134:137], v8, s[0:1] nt
	global_load_dwordx4 v[54:57], v8, s[0:1] offset:256 nt
	s_add_u32 s0, s0, 0x2000
	s_addc_u32 s1, s1, 0
	global_load_dwordx4 v[138:141], v8, s[0:1] nt
	global_load_dwordx4 v[58:61], v8, s[0:1] offset:256 nt
	s_add_u32 s0, s0, 0x2000
	s_addc_u32 s1, s1, 0
	global_load_dwordx4 v[142:145], v8, s[0:1] nt
	global_load_dwordx4 v[62:65], v8, s[0:1] offset:256 nt
	s_mov_b64 exec, 1
	global_atomic_add v18, v16, v17, s[6:7] sc0
	s_mov_b64 exec, -1
	s_waitcnt vmcnt(1)
	v_cvt_pk_bf16_f32 v20, v154, v158
	v_cvt_pk_bf16_f32 v21, v162, v166
	v_cvt_pk_bf16_f32 v22, v170, v174
	v_cvt_pk_bf16_f32 v23, v178, v182
	global_store_dwordx4 v44, v[20:23], s[2:3]
	v_cvt_pk_bf16_f32 v24, v186, v190
	v_cvt_pk_bf16_f32 v25, v194, v198
	v_cvt_pk_bf16_f32 v26, v130, v134
	v_cvt_pk_bf16_f32 v27, v138, v142
	global_store_dwordx4 v44, v[24:27], s[2:3] offset:16
	v_cvt_pk_bf16_f32 v28, v155, v159
	v_cvt_pk_bf16_f32 v29, v163, v167
	v_cvt_pk_bf16_f32 v30, v171, v175
	v_cvt_pk_bf16_f32 v31, v179, v183
	global_store_dwordx4 v45, v[28:31], s[2:3]
	v_cvt_pk_bf16_f32 v32, v187, v191
	v_cvt_pk_bf16_f32 v33, v195, v199
	v_cvt_pk_bf16_f32 v34, v131, v135
	v_cvt_pk_bf16_f32 v35, v139, v143
	global_store_dwordx4 v45, v[32:35], s[2:3] offset:16
	v_cvt_pk_bf16_f32 v36, v156, v160
	v_cvt_pk_bf16_f32 v37, v164, v168
	v_cvt_pk_bf16_f32 v38, v172, v176
	v_cvt_pk_bf16_f32 v39, v180, v184
	global_store_dwordx4 v46, v[36:39], s[2:3]
	v_cvt_pk_bf16_f32 v40, v188, v192
	v_cvt_pk_bf16_f32 v41, v196, v200
	v_cvt_pk_bf16_f32 v42, v132, v136
	v_cvt_pk_bf16_f32 v43, v140, v144
	global_store_dwordx4 v46, v[40:43], s[2:3] offset:16
	v_cvt_pk_bf16_f32 v20, v157, v161
	v_cvt_pk_bf16_f32 v21, v165, v169
	v_cvt_pk_bf16_f32 v22, v173, v177
	v_cvt_pk_bf16_f32 v23, v181, v185
	global_store_dwordx4 v47, v[20:23], s[2:3]
	v_cvt_pk_bf16_f32 v24, v189, v193
	v_cvt_pk_bf16_f32 v25, v197, v201
	v_cvt_pk_bf16_f32 v26, v133, v137
	v_cvt_pk_bf16_f32 v27, v141, v145
	global_store_dwordx4 v47, v[24:27], s[2:3] offset:16
	v_cvt_pk_bf16_f32 v28, v204, v208
	v_cvt_pk_bf16_f32 v29, v212, v216
	v_cvt_pk_bf16_f32 v30, v220, v224
	v_cvt_pk_bf16_f32 v31, v228, v232
	global_store_dwordx4 v44, v[28:31], s[4:5]
	v_cvt_pk_bf16_f32 v32, v236, v240
	v_cvt_pk_bf16_f32 v33, v244, v248
	v_cvt_pk_bf16_f32 v34, v50, v54
	v_cvt_pk_bf16_f32 v35, v58, v62
	global_store_dwordx4 v44, v[32:35], s[4:5] offset:16
	v_cvt_pk_bf16_f32 v36, v205, v209
	v_cvt_pk_bf16_f32 v37, v213, v217
	v_cvt_pk_bf16_f32 v38, v221, v225
	v_cvt_pk_bf16_f32 v39, v229, v233
	global_store_dwordx4 v45, v[36:39], s[4:5]
	v_cvt_pk_bf16_f32 v40, v237, v241
	v_cvt_pk_bf16_f32 v41, v245, v249
	v_cvt_pk_bf16_f32 v42, v51, v55
	v_cvt_pk_bf16_f32 v43, v59, v63
	global_store_dwordx4 v45, v[40:43], s[4:5] offset:16
	v_cvt_pk_bf16_f32 v20, v206, v210
	v_cvt_pk_bf16_f32 v21, v214, v218
	v_cvt_pk_bf16_f32 v22, v222, v226
	v_cvt_pk_bf16_f32 v23, v230, v234
	global_store_dwordx4 v46, v[20:23], s[4:5]
	v_cvt_pk_bf16_f32 v24, v238, v242
	v_cvt_pk_bf16_f32 v25, v246, v250
	v_cvt_pk_bf16_f32 v26, v52, v56
	v_cvt_pk_bf16_f32 v27, v60, v64
	global_store_dwordx4 v46, v[24:27], s[4:5] offset:16
	v_cvt_pk_bf16_f32 v28, v207, v211
	v_cvt_pk_bf16_f32 v29, v215, v219
	v_cvt_pk_bf16_f32 v30, v223, v227
	v_cvt_pk_bf16_f32 v31, v231, v235
	global_store_dwordx4 v47, v[28:31], s[4:5]
	v_cvt_pk_bf16_f32 v32, v239, v243
	v_cvt_pk_bf16_f32 v33, v247, v251
	v_cvt_pk_bf16_f32 v34, v53, v57
	v_cvt_pk_bf16_f32 v35, v61, v65
	global_store_dwordx4 v47, v[32:35], s[4:5] offset:16
	s_waitcnt vmcnt(16)
	s_branch .Lw1d_loop

.LBB0_1229:
	s_or_b64 exec, exec, s[0:1]
	s_waitcnt lgkmcnt(0)
	s_barrier
	ds_read_b32 v1, v155
	s_movk_i32 s0, 0x6cf
	s_waitcnt lgkmcnt(0)
	v_add_u32_e32 v1, s98, v1
	v_cmp_lt_u32_e32 vcc, s0, v1
	v_readfirstlane_b32 s42, v1
	s_mov_b64 s[0:1], -1
	s_cbranch_vccnz .LBB0_1224
	s_cmpk_gt_u32 s42, 0x2ff
	s_cbranch_scc1 .Lq_nomap
	s_cmpk_lt_u32 s42, 0xc0
	s_cbranch_scc1 .Lq_nomap
	s_cmpk_lt_u32 s42, 0x2c0
	s_cbranch_scc1 .Lq_g1
	s_sub_u32 s42, s42, 0x200
	s_branch .Lq_nomap
